# SwiGLU units: the leading half computes and stores its first epilogue group before the alignment barrier (while the trailing half finishes its last MFMA block)
# speedup vs baseline: 1.0039x; 1.0039x over previous
.Lpk354_exit:
	s_mov_b32 s100, 0xbfb8aa3b
	v_pk_mul_f32 v[166:167], v[126:127], s[100:101] op_sel_hi:[1,0]
	v_pk_mul_f32 v[168:169], v[128:129], s[100:101] op_sel_hi:[1,0]
	v_pk_mul_f32 v[170:171], v[122:123], s[100:101] op_sel_hi:[1,0]
	v_pk_mul_f32 v[172:173], v[124:125], s[100:101] op_sel_hi:[1,0]
	v_exp_f32_e32 v166, v166
	v_exp_f32_e32 v167, v167
	v_exp_f32_e32 v168, v168
	v_exp_f32_e32 v169, v169
	v_exp_f32_e32 v170, v170
	v_exp_f32_e32 v171, v171
	v_exp_f32_e32 v172, v172
	v_exp_f32_e32 v173, v173
	v_pk_add_f32 v[166:167], v[166:167], 1.0 op_sel_hi:[1,0]
	v_pk_add_f32 v[168:169], v[168:169], 1.0 op_sel_hi:[1,0]
	v_pk_add_f32 v[170:171], v[170:171], 1.0 op_sel_hi:[1,0]
	v_pk_add_f32 v[172:173], v[172:173], 1.0 op_sel_hi:[1,0]
	v_rcp_f32_e32 v166, v166
	v_rcp_f32_e32 v167, v167
	v_rcp_f32_e32 v168, v168
	v_rcp_f32_e32 v169, v169
	v_rcp_f32_e32 v170, v170
	v_rcp_f32_e32 v171, v171
	v_rcp_f32_e32 v172, v172
	v_rcp_f32_e32 v173, v173
	v_pk_mul_f32 v[166:167], v[126:127], v[166:167]
	v_pk_mul_f32 v[168:169], v[128:129], v[168:169]
	v_pk_mul_f32 v[170:171], v[122:123], v[170:171]
	v_pk_mul_f32 v[172:173], v[124:125], v[172:173]
	v_pk_mul_f32 v[166:167], v[166:167], v[118:119]
	v_pk_mul_f32 v[168:169], v[168:169], v[120:121]
	v_pk_mul_f32 v[170:171], v[170:171], v[114:115]
	v_pk_mul_f32 v[172:173], v[172:173], v[116:117]
	s_lshl_b32 s3, s43, 1
	s_mul_i32 s2, s24, 44
	s_or_b32 s3, s3, s40
	s_add_i32 s2, s3, s2
	s_ashr_i32 s3, s2, 31
	s_lshl_b64 s[2:3], s[2:3], 15
	v_lshl_add_u64 v[148:149], v[140:141], 0, s[2:3]
	v_cvt_pk_bf16_f32 v114, v166, v167
	v_cvt_pk_bf16_f32 v115, v168, v169
	v_cvt_pk_bf16_f32 v116, v170, v171
	v_cvt_pk_bf16_f32 v117, v172, v173
	global_store_dwordx4 v[148:149], v[114:117], off
	s_and_b64 vcc, exec, s[8:9]
	s_cbranch_vccz .LBB0_357
	s_barrier
.LBB0_357:
	v_pk_mul_f32 v[166:167], v[110:111], s[100:101] op_sel_hi:[1,0]
	v_pk_mul_f32 v[168:169], v[112:113], s[100:101] op_sel_hi:[1,0]
	v_pk_mul_f32 v[170:171], v[106:107], s[100:101] op_sel_hi:[1,0]
	v_pk_mul_f32 v[172:173], v[108:109], s[100:101] op_sel_hi:[1,0]
	v_exp_f32_e32 v166, v166
	v_exp_f32_e32 v167, v167
	v_exp_f32_e32 v168, v168
	v_exp_f32_e32 v169, v169
	v_exp_f32_e32 v170, v170
	v_exp_f32_e32 v171, v171
	v_exp_f32_e32 v172, v172
	v_exp_f32_e32 v173, v173
	v_pk_add_f32 v[166:167], v[166:167], 1.0 op_sel_hi:[1,0]
	v_pk_add_f32 v[168:169], v[168:169], 1.0 op_sel_hi:[1,0]
	v_pk_add_f32 v[170:171], v[170:171], 1.0 op_sel_hi:[1,0]
	v_pk_add_f32 v[172:173], v[172:173], 1.0 op_sel_hi:[1,0]
	v_rcp_f32_e32 v166, v166
	v_rcp_f32_e32 v167, v167
	v_rcp_f32_e32 v168, v168
	v_rcp_f32_e32 v169, v169
	v_rcp_f32_e32 v170, v170
	v_rcp_f32_e32 v171, v171
	v_rcp_f32_e32 v172, v172
	v_rcp_f32_e32 v173, v173
	v_pk_mul_f32 v[166:167], v[110:111], v[166:167]
	v_pk_mul_f32 v[168:169], v[112:113], v[168:169]
	v_pk_mul_f32 v[170:171], v[106:107], v[170:171]
	v_pk_mul_f32 v[172:173], v[108:109], v[172:173]
	v_pk_mul_f32 v[166:167], v[166:167], v[102:103]
	v_pk_mul_f32 v[168:169], v[168:169], v[104:105]
	v_pk_mul_f32 v[170:171], v[170:171], v[98:99]
	v_pk_mul_f32 v[172:173], v[172:173], v[100:101]
	s_movk_i32 s2, 0x1000
	v_cvt_pk_bf16_f32 v98, v166, v167
	v_cvt_pk_bf16_f32 v99, v168, v169
	v_cvt_pk_bf16_f32 v100, v170, v171
	v_cvt_pk_bf16_f32 v101, v172, v173
	global_store_dwordx4 v[148:149], v[98:101], off offset:2048
	v_pk_mul_f32 v[166:167], v[94:95], s[100:101] op_sel_hi:[1,0]
	v_pk_mul_f32 v[168:169], v[96:97], s[100:101] op_sel_hi:[1,0]
	v_pk_mul_f32 v[170:171], v[90:91], s[100:101] op_sel_hi:[1,0]
	v_pk_mul_f32 v[172:173], v[92:93], s[100:101] op_sel_hi:[1,0]
	v_exp_f32_e32 v166, v166
	v_exp_f32_e32 v167, v167
	v_exp_f32_e32 v168, v168
	v_exp_f32_e32 v169, v169
	v_exp_f32_e32 v170, v170
	v_exp_f32_e32 v171, v171
	v_exp_f32_e32 v172, v172
	v_exp_f32_e32 v173, v173
	v_pk_add_f32 v[166:167], v[166:167], 1.0 op_sel_hi:[1,0]
	v_pk_add_f32 v[168:169], v[168:169], 1.0 op_sel_hi:[1,0]
	v_pk_add_f32 v[170:171], v[170:171], 1.0 op_sel_hi:[1,0]
	v_pk_add_f32 v[172:173], v[172:173], 1.0 op_sel_hi:[1,0]
	v_rcp_f32_e32 v166, v166
	v_rcp_f32_e32 v167, v167
	v_rcp_f32_e32 v168, v168
	v_rcp_f32_e32 v169, v169
	v_rcp_f32_e32 v170, v170
	v_rcp_f32_e32 v171, v171
	v_rcp_f32_e32 v172, v172
	v_rcp_f32_e32 v173, v173
	v_pk_mul_f32 v[166:167], v[94:95], v[166:167]
	v_pk_mul_f32 v[168:169], v[96:97], v[168:169]
	v_pk_mul_f32 v[170:171], v[90:91], v[170:171]
	v_pk_mul_f32 v[172:173], v[92:93], v[172:173]
	v_pk_mul_f32 v[166:167], v[166:167], v[86:87]
	v_pk_mul_f32 v[168:169], v[168:169], v[88:89]
	v_pk_mul_f32 v[170:171], v[170:171], v[82:83]
	v_pk_mul_f32 v[172:173], v[172:173], v[84:85]
	v_add_co_u32_e32 v86, vcc, s2, v148
	s_nop 1
	v_addc_co_u32_e32 v87, vcc, 0, v149, vcc
	v_cvt_pk_bf16_f32 v82, v166, v167
	v_cvt_pk_bf16_f32 v83, v168, v169
	v_cvt_pk_bf16_f32 v84, v170, v171
	v_cvt_pk_bf16_f32 v85, v172, v173
	global_store_dwordx4 v[86:87], v[82:85], off
	v_pk_mul_f32 v[166:167], v[78:79], s[100:101] op_sel_hi:[1,0]
	v_pk_mul_f32 v[168:169], v[80:81], s[100:101] op_sel_hi:[1,0]
	v_pk_mul_f32 v[170:171], v[74:75], s[100:101] op_sel_hi:[1,0]
	v_pk_mul_f32 v[172:173], v[76:77], s[100:101] op_sel_hi:[1,0]
	v_exp_f32_e32 v166, v166
	v_exp_f32_e32 v167, v167
	v_exp_f32_e32 v168, v168
	v_exp_f32_e32 v169, v169
	v_exp_f32_e32 v170, v170
	v_exp_f32_e32 v171, v171
	v_exp_f32_e32 v172, v172
	v_exp_f32_e32 v173, v173
	v_pk_add_f32 v[166:167], v[166:167], 1.0 op_sel_hi:[1,0]
	v_pk_add_f32 v[168:169], v[168:169], 1.0 op_sel_hi:[1,0]
	v_pk_add_f32 v[170:171], v[170:171], 1.0 op_sel_hi:[1,0]
	v_pk_add_f32 v[172:173], v[172:173], 1.0 op_sel_hi:[1,0]
	v_rcp_f32_e32 v166, v166
	v_rcp_f32_e32 v167, v167
	v_rcp_f32_e32 v168, v168
	v_rcp_f32_e32 v169, v169
	v_rcp_f32_e32 v170, v170
	v_rcp_f32_e32 v171, v171
	v_rcp_f32_e32 v172, v172
	v_rcp_f32_e32 v173, v173
	v_pk_mul_f32 v[166:167], v[78:79], v[166:167]
	v_pk_mul_f32 v[168:169], v[80:81], v[168:169]
	v_pk_mul_f32 v[170:171], v[74:75], v[170:171]
	v_pk_mul_f32 v[172:173], v[76:77], v[172:173]
	v_pk_mul_f32 v[166:167], v[166:167], v[70:71]
	v_pk_mul_f32 v[168:169], v[168:169], v[72:73]
	v_pk_mul_f32 v[170:171], v[170:171], v[66:67]
	v_pk_mul_f32 v[172:173], v[172:173], v[68:69]
	s_movk_i32 s2, 0x4000
	v_cvt_pk_bf16_f32 v66, v166, v167
	v_cvt_pk_bf16_f32 v67, v168, v169
	v_cvt_pk_bf16_f32 v68, v170, v171
	v_cvt_pk_bf16_f32 v69, v172, v173
	global_store_dwordx4 v[86:87], v[66:69], off offset:2048
	v_pk_mul_f32 v[166:167], v[62:63], s[100:101] op_sel_hi:[1,0]
	v_pk_mul_f32 v[168:169], v[64:65], s[100:101] op_sel_hi:[1,0]
	v_pk_mul_f32 v[170:171], v[58:59], s[100:101] op_sel_hi:[1,0]
	v_pk_mul_f32 v[172:173], v[60:61], s[100:101] op_sel_hi:[1,0]
	v_exp_f32_e32 v166, v166
	v_exp_f32_e32 v167, v167
	v_exp_f32_e32 v168, v168
	v_exp_f32_e32 v169, v169
	v_exp_f32_e32 v170, v170
	v_exp_f32_e32 v171, v171
	v_exp_f32_e32 v172, v172
	v_exp_f32_e32 v173, v173
	v_pk_add_f32 v[166:167], v[166:167], 1.0 op_sel_hi:[1,0]
	v_pk_add_f32 v[168:169], v[168:169], 1.0 op_sel_hi:[1,0]
	v_pk_add_f32 v[170:171], v[170:171], 1.0 op_sel_hi:[1,0]
	v_pk_add_f32 v[172:173], v[172:173], 1.0 op_sel_hi:[1,0]
	v_rcp_f32_e32 v166, v166
	v_rcp_f32_e32 v167, v167
	v_rcp_f32_e32 v168, v168
	v_rcp_f32_e32 v169, v169
	v_rcp_f32_e32 v170, v170
	v_rcp_f32_e32 v171, v171
	v_rcp_f32_e32 v172, v172
	v_rcp_f32_e32 v173, v173
	v_pk_mul_f32 v[166:167], v[62:63], v[166:167]
	v_pk_mul_f32 v[168:169], v[64:65], v[168:169]
	v_pk_mul_f32 v[170:171], v[58:59], v[170:171]
	v_pk_mul_f32 v[172:173], v[60:61], v[172:173]
	v_pk_mul_f32 v[166:167], v[166:167], v[54:55]
	v_pk_mul_f32 v[168:169], v[168:169], v[56:57]
	v_pk_mul_f32 v[170:171], v[170:171], v[50:51]
	v_pk_mul_f32 v[172:173], v[172:173], v[52:53]
	v_add_co_u32_e32 v54, vcc, s2, v148
	s_nop 1
	v_addc_co_u32_e32 v55, vcc, 0, v149, vcc
	s_movk_i32 s2, 0x5000
	v_add_co_u32_e32 v56, vcc, s2, v148
	s_nop 0
	s_nop 1
	v_addc_co_u32_e32 v57, vcc, 0, v149, vcc
	v_cvt_pk_bf16_f32 v50, v166, v167
	v_cvt_pk_bf16_f32 v51, v168, v169
	v_cvt_pk_bf16_f32 v52, v170, v171
	v_cvt_pk_bf16_f32 v53, v172, v173
	global_store_dwordx4 v[56:57], v[50:53], off offset:-4096
	v_pk_mul_f32 v[166:167], v[46:47], s[100:101] op_sel_hi:[1,0]
	v_pk_mul_f32 v[168:169], v[48:49], s[100:101] op_sel_hi:[1,0]
	v_pk_mul_f32 v[170:171], v[42:43], s[100:101] op_sel_hi:[1,0]
	v_pk_mul_f32 v[172:173], v[44:45], s[100:101] op_sel_hi:[1,0]
	v_exp_f32_e32 v166, v166
	v_exp_f32_e32 v167, v167
	v_exp_f32_e32 v168, v168
	v_exp_f32_e32 v169, v169
	v_exp_f32_e32 v170, v170
	v_exp_f32_e32 v171, v171
	v_exp_f32_e32 v172, v172
	v_exp_f32_e32 v173, v173
	v_pk_add_f32 v[166:167], v[166:167], 1.0 op_sel_hi:[1,0]
	v_pk_add_f32 v[168:169], v[168:169], 1.0 op_sel_hi:[1,0]
	v_pk_add_f32 v[170:171], v[170:171], 1.0 op_sel_hi:[1,0]
	v_pk_add_f32 v[172:173], v[172:173], 1.0 op_sel_hi:[1,0]
	v_rcp_f32_e32 v166, v166
	v_rcp_f32_e32 v167, v167
	v_rcp_f32_e32 v168, v168
	v_rcp_f32_e32 v169, v169
	v_rcp_f32_e32 v170, v170
	v_rcp_f32_e32 v171, v171
	v_rcp_f32_e32 v172, v172
	v_rcp_f32_e32 v173, v173
	v_pk_mul_f32 v[166:167], v[46:47], v[166:167]
	v_pk_mul_f32 v[168:169], v[48:49], v[168:169]
	v_pk_mul_f32 v[170:171], v[42:43], v[170:171]
	v_pk_mul_f32 v[172:173], v[44:45], v[172:173]
	v_pk_mul_f32 v[166:167], v[166:167], v[38:39]
	v_pk_mul_f32 v[168:169], v[168:169], v[40:41]
	v_pk_mul_f32 v[170:171], v[170:171], v[34:35]
	v_pk_mul_f32 v[172:173], v[172:173], v[36:37]
	s_andn2_b64 vcc, exec, s[18:19]
	v_cvt_pk_bf16_f32 v34, v166, v167
	v_cvt_pk_bf16_f32 v35, v168, v169
	v_cvt_pk_bf16_f32 v36, v170, v171
	v_cvt_pk_bf16_f32 v37, v172, v173
	global_store_dwordx4 v[54:55], v[34:37], off offset:2048
	v_pk_mul_f32 v[166:167], v[30:31], s[100:101] op_sel_hi:[1,0]
	v_pk_mul_f32 v[168:169], v[32:33], s[100:101] op_sel_hi:[1,0]
	v_pk_mul_f32 v[170:171], v[26:27], s[100:101] op_sel_hi:[1,0]
	v_pk_mul_f32 v[172:173], v[28:29], s[100:101] op_sel_hi:[1,0]
	v_exp_f32_e32 v166, v166
	v_exp_f32_e32 v167, v167
	v_exp_f32_e32 v168, v168
	v_exp_f32_e32 v169, v169
	v_exp_f32_e32 v170, v170
	v_exp_f32_e32 v171, v171
	v_exp_f32_e32 v172, v172
	v_exp_f32_e32 v173, v173
	v_pk_add_f32 v[166:167], v[166:167], 1.0 op_sel_hi:[1,0]
	v_pk_add_f32 v[168:169], v[168:169], 1.0 op_sel_hi:[1,0]
	v_pk_add_f32 v[170:171], v[170:171], 1.0 op_sel_hi:[1,0]
	v_pk_add_f32 v[172:173], v[172:173], 1.0 op_sel_hi:[1,0]
	v_rcp_f32_e32 v166, v166
	v_rcp_f32_e32 v167, v167
	v_rcp_f32_e32 v168, v168
	v_rcp_f32_e32 v169, v169
	v_rcp_f32_e32 v170, v170
	v_rcp_f32_e32 v171, v171
	v_rcp_f32_e32 v172, v172
	v_rcp_f32_e32 v173, v173
	v_pk_mul_f32 v[166:167], v[30:31], v[166:167]
	v_pk_mul_f32 v[168:169], v[32:33], v[168:169]
	v_pk_mul_f32 v[170:171], v[26:27], v[170:171]
	v_pk_mul_f32 v[172:173], v[28:29], v[172:173]
	v_pk_mul_f32 v[166:167], v[166:167], v[22:23]
	v_pk_mul_f32 v[168:169], v[168:169], v[24:25]
	v_pk_mul_f32 v[170:171], v[170:171], v[18:19]
	v_pk_mul_f32 v[172:173], v[172:173], v[20:21]
	s_mov_b64 s[2:3], -1
	v_cvt_pk_bf16_f32 v18, v166, v167
	v_cvt_pk_bf16_f32 v19, v168, v169
	v_cvt_pk_bf16_f32 v20, v170, v171
	v_cvt_pk_bf16_f32 v21, v172, v173
	global_store_dwordx4 v[56:57], v[18:21], off
	v_pk_mul_f32 v[166:167], v[14:15], s[100:101] op_sel_hi:[1,0]
	v_pk_mul_f32 v[168:169], v[16:17], s[100:101] op_sel_hi:[1,0]
	v_pk_mul_f32 v[170:171], v[10:11], s[100:101] op_sel_hi:[1,0]
	v_pk_mul_f32 v[172:173], v[12:13], s[100:101] op_sel_hi:[1,0]
	v_exp_f32_e32 v166, v166
	v_exp_f32_e32 v167, v167
	v_exp_f32_e32 v168, v168
	v_exp_f32_e32 v169, v169
	v_exp_f32_e32 v170, v170
	v_exp_f32_e32 v171, v171
	v_exp_f32_e32 v172, v172
	v_exp_f32_e32 v173, v173
	v_pk_add_f32 v[166:167], v[166:167], 1.0 op_sel_hi:[1,0]
	v_pk_add_f32 v[168:169], v[168:169], 1.0 op_sel_hi:[1,0]
	v_pk_add_f32 v[170:171], v[170:171], 1.0 op_sel_hi:[1,0]
	v_pk_add_f32 v[172:173], v[172:173], 1.0 op_sel_hi:[1,0]
	v_rcp_f32_e32 v166, v166
	v_rcp_f32_e32 v167, v167
	v_rcp_f32_e32 v168, v168
	v_rcp_f32_e32 v169, v169
	v_rcp_f32_e32 v170, v170
	v_rcp_f32_e32 v171, v171
	v_rcp_f32_e32 v172, v172
	v_rcp_f32_e32 v173, v173
	v_pk_mul_f32 v[166:167], v[14:15], v[166:167]
	v_pk_mul_f32 v[168:169], v[16:17], v[168:169]
	v_pk_mul_f32 v[170:171], v[10:11], v[170:171]
	v_pk_mul_f32 v[172:173], v[12:13], v[172:173]
	v_pk_mul_f32 v[166:167], v[166:167], v[6:7]
	v_pk_mul_f32 v[168:169], v[168:169], v[8:9]
	v_pk_mul_f32 v[170:171], v[170:171], v[2:3]
	v_pk_mul_f32 v[172:173], v[172:173], v[4:5]
	v_cvt_pk_bf16_f32 v2, v166, v167
	v_cvt_pk_bf16_f32 v3, v168, v169
	v_cvt_pk_bf16_f32 v4, v170, v171
	v_cvt_pk_bf16_f32 v5, v172, v173
	global_store_dwordx4 v[56:57], v[2:5], off offset:2048
	s_cbranch_vccnz .LBB0_349
	s_andn2_b64 vcc, exec, s[0:1]
	s_cbranch_vccnz .LBB0_348
	s_barrier
	s_branch .LBB0_348

.Lpk451_exit:
	s_mov_b32 s100, 0xbfb8aa3b
	v_pk_mul_f32 v[152:153], v[126:127], s[100:101] op_sel_hi:[1,0]
	v_pk_mul_f32 v[154:155], v[128:129], s[100:101] op_sel_hi:[1,0]
	v_pk_mul_f32 v[156:157], v[122:123], s[100:101] op_sel_hi:[1,0]
	v_pk_mul_f32 v[158:159], v[124:125], s[100:101] op_sel_hi:[1,0]
	v_exp_f32_e32 v152, v152
	v_exp_f32_e32 v153, v153
	v_exp_f32_e32 v154, v154
	v_exp_f32_e32 v155, v155
	v_exp_f32_e32 v156, v156
	v_exp_f32_e32 v157, v157
	v_exp_f32_e32 v158, v158
	v_exp_f32_e32 v159, v159
	v_pk_add_f32 v[152:153], v[152:153], 1.0 op_sel_hi:[1,0]
	v_pk_add_f32 v[154:155], v[154:155], 1.0 op_sel_hi:[1,0]
	v_pk_add_f32 v[156:157], v[156:157], 1.0 op_sel_hi:[1,0]
	v_pk_add_f32 v[158:159], v[158:159], 1.0 op_sel_hi:[1,0]
	v_rcp_f32_e32 v152, v152
	v_rcp_f32_e32 v153, v153
	v_rcp_f32_e32 v154, v154
	v_rcp_f32_e32 v155, v155
	v_rcp_f32_e32 v156, v156
	v_rcp_f32_e32 v157, v157
	v_rcp_f32_e32 v158, v158
	v_rcp_f32_e32 v159, v159
	v_pk_mul_f32 v[152:153], v[126:127], v[152:153]
	v_pk_mul_f32 v[154:155], v[128:129], v[154:155]
	v_pk_mul_f32 v[156:157], v[122:123], v[156:157]
	v_pk_mul_f32 v[158:159], v[124:125], v[158:159]
	v_pk_mul_f32 v[152:153], v[152:153], v[118:119]
	v_pk_mul_f32 v[154:155], v[154:155], v[120:121]
	v_pk_mul_f32 v[156:157], v[156:157], v[114:115]
	v_pk_mul_f32 v[158:159], v[158:159], v[116:117]
	s_lshl_b32 s3, s24, 1
	s_mul_i32 s2, s26, 44
	s_or_b32 s3, s3, s41
	s_add_i32 s2, s3, s2
	s_ashr_i32 s3, s2, 31
	s_lshl_b64 s[2:3], s[2:3], 15
	v_lshl_add_u64 v[146:147], v[138:139], 0, s[2:3]
	v_cvt_pk_bf16_f32 v114, v152, v153
	v_cvt_pk_bf16_f32 v115, v154, v155
	v_cvt_pk_bf16_f32 v116, v156, v157
	v_cvt_pk_bf16_f32 v117, v158, v159
	global_store_dwordx4 v[146:147], v[114:117], off
	s_and_b64 vcc, exec, s[8:9]
	s_cbranch_vccz .LBB0_454
	s_barrier
.LBB0_454:
	v_pk_mul_f32 v[152:153], v[110:111], s[100:101] op_sel_hi:[1,0]
	v_pk_mul_f32 v[154:155], v[112:113], s[100:101] op_sel_hi:[1,0]
	v_pk_mul_f32 v[156:157], v[106:107], s[100:101] op_sel_hi:[1,0]
	v_pk_mul_f32 v[158:159], v[108:109], s[100:101] op_sel_hi:[1,0]
	v_exp_f32_e32 v152, v152
	v_exp_f32_e32 v153, v153
	v_exp_f32_e32 v154, v154
	v_exp_f32_e32 v155, v155
	v_exp_f32_e32 v156, v156
	v_exp_f32_e32 v157, v157
	v_exp_f32_e32 v158, v158
	v_exp_f32_e32 v159, v159
	v_pk_add_f32 v[152:153], v[152:153], 1.0 op_sel_hi:[1,0]
	v_pk_add_f32 v[154:155], v[154:155], 1.0 op_sel_hi:[1,0]
	v_pk_add_f32 v[156:157], v[156:157], 1.0 op_sel_hi:[1,0]
	v_pk_add_f32 v[158:159], v[158:159], 1.0 op_sel_hi:[1,0]
	v_rcp_f32_e32 v152, v152
	v_rcp_f32_e32 v153, v153
	v_rcp_f32_e32 v154, v154
	v_rcp_f32_e32 v155, v155
	v_rcp_f32_e32 v156, v156
	v_rcp_f32_e32 v157, v157
	v_rcp_f32_e32 v158, v158
	v_rcp_f32_e32 v159, v159
	v_pk_mul_f32 v[152:153], v[110:111], v[152:153]
	v_pk_mul_f32 v[154:155], v[112:113], v[154:155]
	v_pk_mul_f32 v[156:157], v[106:107], v[156:157]
	v_pk_mul_f32 v[158:159], v[108:109], v[158:159]
	v_pk_mul_f32 v[152:153], v[152:153], v[102:103]
	v_pk_mul_f32 v[154:155], v[154:155], v[104:105]
	v_pk_mul_f32 v[156:157], v[156:157], v[98:99]
	v_pk_mul_f32 v[158:159], v[158:159], v[100:101]
	s_movk_i32 s2, 0x1000
	v_cvt_pk_bf16_f32 v98, v152, v153
	v_cvt_pk_bf16_f32 v99, v154, v155
	v_cvt_pk_bf16_f32 v100, v156, v157
	v_cvt_pk_bf16_f32 v101, v158, v159
	global_store_dwordx4 v[146:147], v[98:101], off offset:2048
	v_pk_mul_f32 v[152:153], v[94:95], s[100:101] op_sel_hi:[1,0]
	v_pk_mul_f32 v[154:155], v[96:97], s[100:101] op_sel_hi:[1,0]
	v_pk_mul_f32 v[156:157], v[90:91], s[100:101] op_sel_hi:[1,0]
	v_pk_mul_f32 v[158:159], v[92:93], s[100:101] op_sel_hi:[1,0]
	v_exp_f32_e32 v152, v152
	v_exp_f32_e32 v153, v153
	v_exp_f32_e32 v154, v154
	v_exp_f32_e32 v155, v155
	v_exp_f32_e32 v156, v156
	v_exp_f32_e32 v157, v157
	v_exp_f32_e32 v158, v158
	v_exp_f32_e32 v159, v159
	v_pk_add_f32 v[152:153], v[152:153], 1.0 op_sel_hi:[1,0]
	v_pk_add_f32 v[154:155], v[154:155], 1.0 op_sel_hi:[1,0]
	v_pk_add_f32 v[156:157], v[156:157], 1.0 op_sel_hi:[1,0]
	v_pk_add_f32 v[158:159], v[158:159], 1.0 op_sel_hi:[1,0]
	v_rcp_f32_e32 v152, v152
	v_rcp_f32_e32 v153, v153
	v_rcp_f32_e32 v154, v154
	v_rcp_f32_e32 v155, v155
	v_rcp_f32_e32 v156, v156
	v_rcp_f32_e32 v157, v157
	v_rcp_f32_e32 v158, v158
	v_rcp_f32_e32 v159, v159
	v_pk_mul_f32 v[152:153], v[94:95], v[152:153]
	v_pk_mul_f32 v[154:155], v[96:97], v[154:155]
	v_pk_mul_f32 v[156:157], v[90:91], v[156:157]
	v_pk_mul_f32 v[158:159], v[92:93], v[158:159]
	v_pk_mul_f32 v[152:153], v[152:153], v[86:87]
	v_pk_mul_f32 v[154:155], v[154:155], v[88:89]
	v_pk_mul_f32 v[156:157], v[156:157], v[82:83]
	v_pk_mul_f32 v[158:159], v[158:159], v[84:85]
	v_add_co_u32_e32 v86, vcc, s2, v146
	s_nop 1
	v_addc_co_u32_e32 v87, vcc, 0, v147, vcc
	v_cvt_pk_bf16_f32 v82, v152, v153
	v_cvt_pk_bf16_f32 v83, v154, v155
	v_cvt_pk_bf16_f32 v84, v156, v157
	v_cvt_pk_bf16_f32 v85, v158, v159
	global_store_dwordx4 v[86:87], v[82:85], off
	v_pk_mul_f32 v[152:153], v[78:79], s[100:101] op_sel_hi:[1,0]
	v_pk_mul_f32 v[154:155], v[80:81], s[100:101] op_sel_hi:[1,0]
	v_pk_mul_f32 v[156:157], v[74:75], s[100:101] op_sel_hi:[1,0]
	v_pk_mul_f32 v[158:159], v[76:77], s[100:101] op_sel_hi:[1,0]
	v_exp_f32_e32 v152, v152
	v_exp_f32_e32 v153, v153
	v_exp_f32_e32 v154, v154
	v_exp_f32_e32 v155, v155
	v_exp_f32_e32 v156, v156
	v_exp_f32_e32 v157, v157
	v_exp_f32_e32 v158, v158
	v_exp_f32_e32 v159, v159
	v_pk_add_f32 v[152:153], v[152:153], 1.0 op_sel_hi:[1,0]
	v_pk_add_f32 v[154:155], v[154:155], 1.0 op_sel_hi:[1,0]
	v_pk_add_f32 v[156:157], v[156:157], 1.0 op_sel_hi:[1,0]
	v_pk_add_f32 v[158:159], v[158:159], 1.0 op_sel_hi:[1,0]
	v_rcp_f32_e32 v152, v152
	v_rcp_f32_e32 v153, v153
	v_rcp_f32_e32 v154, v154
	v_rcp_f32_e32 v155, v155
	v_rcp_f32_e32 v156, v156
	v_rcp_f32_e32 v157, v157
	v_rcp_f32_e32 v158, v158
	v_rcp_f32_e32 v159, v159
	v_pk_mul_f32 v[152:153], v[78:79], v[152:153]
	v_pk_mul_f32 v[154:155], v[80:81], v[154:155]
	v_pk_mul_f32 v[156:157], v[74:75], v[156:157]
	v_pk_mul_f32 v[158:159], v[76:77], v[158:159]
	v_pk_mul_f32 v[152:153], v[152:153], v[70:71]
	v_pk_mul_f32 v[154:155], v[154:155], v[72:73]
	v_pk_mul_f32 v[156:157], v[156:157], v[66:67]
	v_pk_mul_f32 v[158:159], v[158:159], v[68:69]
	s_movk_i32 s2, 0x4000
	v_cvt_pk_bf16_f32 v66, v152, v153
	v_cvt_pk_bf16_f32 v67, v154, v155
	v_cvt_pk_bf16_f32 v68, v156, v157
	v_cvt_pk_bf16_f32 v69, v158, v159
	global_store_dwordx4 v[86:87], v[66:69], off offset:2048
	v_pk_mul_f32 v[152:153], v[62:63], s[100:101] op_sel_hi:[1,0]
	v_pk_mul_f32 v[154:155], v[64:65], s[100:101] op_sel_hi:[1,0]
	v_pk_mul_f32 v[156:157], v[58:59], s[100:101] op_sel_hi:[1,0]
	v_pk_mul_f32 v[158:159], v[60:61], s[100:101] op_sel_hi:[1,0]
	v_exp_f32_e32 v152, v152
	v_exp_f32_e32 v153, v153
	v_exp_f32_e32 v154, v154
	v_exp_f32_e32 v155, v155
	v_exp_f32_e32 v156, v156
	v_exp_f32_e32 v157, v157
	v_exp_f32_e32 v158, v158
	v_exp_f32_e32 v159, v159
	v_pk_add_f32 v[152:153], v[152:153], 1.0 op_sel_hi:[1,0]
	v_pk_add_f32 v[154:155], v[154:155], 1.0 op_sel_hi:[1,0]
	v_pk_add_f32 v[156:157], v[156:157], 1.0 op_sel_hi:[1,0]
	v_pk_add_f32 v[158:159], v[158:159], 1.0 op_sel_hi:[1,0]
	v_rcp_f32_e32 v152, v152
	v_rcp_f32_e32 v153, v153
	v_rcp_f32_e32 v154, v154
	v_rcp_f32_e32 v155, v155
	v_rcp_f32_e32 v156, v156
	v_rcp_f32_e32 v157, v157
	v_rcp_f32_e32 v158, v158
	v_rcp_f32_e32 v159, v159
	v_pk_mul_f32 v[152:153], v[62:63], v[152:153]
	v_pk_mul_f32 v[154:155], v[64:65], v[154:155]
	v_pk_mul_f32 v[156:157], v[58:59], v[156:157]
	v_pk_mul_f32 v[158:159], v[60:61], v[158:159]
	v_pk_mul_f32 v[152:153], v[152:153], v[54:55]
	v_pk_mul_f32 v[154:155], v[154:155], v[56:57]
	v_pk_mul_f32 v[156:157], v[156:157], v[50:51]
	v_pk_mul_f32 v[158:159], v[158:159], v[52:53]
	v_add_co_u32_e32 v54, vcc, s2, v146
	s_nop 1
	v_addc_co_u32_e32 v55, vcc, 0, v147, vcc
	s_movk_i32 s2, 0x5000
	v_add_co_u32_e32 v56, vcc, s2, v146
	s_nop 0
	s_nop 1
	v_addc_co_u32_e32 v57, vcc, 0, v147, vcc
	v_cvt_pk_bf16_f32 v50, v152, v153
	v_cvt_pk_bf16_f32 v51, v154, v155
	v_cvt_pk_bf16_f32 v52, v156, v157
	v_cvt_pk_bf16_f32 v53, v158, v159
	global_store_dwordx4 v[56:57], v[50:53], off offset:-4096
	v_pk_mul_f32 v[152:153], v[46:47], s[100:101] op_sel_hi:[1,0]
	v_pk_mul_f32 v[154:155], v[48:49], s[100:101] op_sel_hi:[1,0]
	v_pk_mul_f32 v[156:157], v[42:43], s[100:101] op_sel_hi:[1,0]
	v_pk_mul_f32 v[158:159], v[44:45], s[100:101] op_sel_hi:[1,0]
	v_exp_f32_e32 v152, v152
	v_exp_f32_e32 v153, v153
	v_exp_f32_e32 v154, v154
	v_exp_f32_e32 v155, v155
	v_exp_f32_e32 v156, v156
	v_exp_f32_e32 v157, v157
	v_exp_f32_e32 v158, v158
	v_exp_f32_e32 v159, v159
	v_pk_add_f32 v[152:153], v[152:153], 1.0 op_sel_hi:[1,0]
	v_pk_add_f32 v[154:155], v[154:155], 1.0 op_sel_hi:[1,0]
	v_pk_add_f32 v[156:157], v[156:157], 1.0 op_sel_hi:[1,0]
	v_pk_add_f32 v[158:159], v[158:159], 1.0 op_sel_hi:[1,0]
	v_rcp_f32_e32 v152, v152
	v_rcp_f32_e32 v153, v153
	v_rcp_f32_e32 v154, v154
	v_rcp_f32_e32 v155, v155
	v_rcp_f32_e32 v156, v156
	v_rcp_f32_e32 v157, v157
	v_rcp_f32_e32 v158, v158
	v_rcp_f32_e32 v159, v159
	v_pk_mul_f32 v[152:153], v[46:47], v[152:153]
	v_pk_mul_f32 v[154:155], v[48:49], v[154:155]
	v_pk_mul_f32 v[156:157], v[42:43], v[156:157]
	v_pk_mul_f32 v[158:159], v[44:45], v[158:159]
	v_pk_mul_f32 v[152:153], v[152:153], v[38:39]
	v_pk_mul_f32 v[154:155], v[154:155], v[40:41]
	v_pk_mul_f32 v[156:157], v[156:157], v[34:35]
	v_pk_mul_f32 v[158:159], v[158:159], v[36:37]
	s_andn2_b64 vcc, exec, s[18:19]
	v_cvt_pk_bf16_f32 v34, v152, v153
	v_cvt_pk_bf16_f32 v35, v154, v155
	v_cvt_pk_bf16_f32 v36, v156, v157
	v_cvt_pk_bf16_f32 v37, v158, v159
	global_store_dwordx4 v[54:55], v[34:37], off offset:2048
	v_pk_mul_f32 v[152:153], v[30:31], s[100:101] op_sel_hi:[1,0]
	v_pk_mul_f32 v[154:155], v[32:33], s[100:101] op_sel_hi:[1,0]
	v_pk_mul_f32 v[156:157], v[26:27], s[100:101] op_sel_hi:[1,0]
	v_pk_mul_f32 v[158:159], v[28:29], s[100:101] op_sel_hi:[1,0]
	v_exp_f32_e32 v152, v152
	v_exp_f32_e32 v153, v153
	v_exp_f32_e32 v154, v154
	v_exp_f32_e32 v155, v155
	v_exp_f32_e32 v156, v156
	v_exp_f32_e32 v157, v157
	v_exp_f32_e32 v158, v158
	v_exp_f32_e32 v159, v159
	v_pk_add_f32 v[152:153], v[152:153], 1.0 op_sel_hi:[1,0]
	v_pk_add_f32 v[154:155], v[154:155], 1.0 op_sel_hi:[1,0]
	v_pk_add_f32 v[156:157], v[156:157], 1.0 op_sel_hi:[1,0]
	v_pk_add_f32 v[158:159], v[158:159], 1.0 op_sel_hi:[1,0]
	v_rcp_f32_e32 v152, v152
	v_rcp_f32_e32 v153, v153
	v_rcp_f32_e32 v154, v154
	v_rcp_f32_e32 v155, v155
	v_rcp_f32_e32 v156, v156
	v_rcp_f32_e32 v157, v157
	v_rcp_f32_e32 v158, v158
	v_rcp_f32_e32 v159, v159
	v_pk_mul_f32 v[152:153], v[30:31], v[152:153]
	v_pk_mul_f32 v[154:155], v[32:33], v[154:155]
	v_pk_mul_f32 v[156:157], v[26:27], v[156:157]
	v_pk_mul_f32 v[158:159], v[28:29], v[158:159]
	v_pk_mul_f32 v[152:153], v[152:153], v[22:23]
	v_pk_mul_f32 v[154:155], v[154:155], v[24:25]
	v_pk_mul_f32 v[156:157], v[156:157], v[18:19]
	v_pk_mul_f32 v[158:159], v[158:159], v[20:21]
	s_mov_b64 s[2:3], -1
	v_cvt_pk_bf16_f32 v18, v152, v153
	v_cvt_pk_bf16_f32 v19, v154, v155
	v_cvt_pk_bf16_f32 v20, v156, v157
	v_cvt_pk_bf16_f32 v21, v158, v159
	global_store_dwordx4 v[56:57], v[18:21], off
	v_pk_mul_f32 v[152:153], v[14:15], s[100:101] op_sel_hi:[1,0]
	v_pk_mul_f32 v[154:155], v[16:17], s[100:101] op_sel_hi:[1,0]
	v_pk_mul_f32 v[156:157], v[10:11], s[100:101] op_sel_hi:[1,0]
	v_pk_mul_f32 v[158:159], v[12:13], s[100:101] op_sel_hi:[1,0]
	v_exp_f32_e32 v152, v152
	v_exp_f32_e32 v153, v153
	v_exp_f32_e32 v154, v154
	v_exp_f32_e32 v155, v155
	v_exp_f32_e32 v156, v156
	v_exp_f32_e32 v157, v157
	v_exp_f32_e32 v158, v158
	v_exp_f32_e32 v159, v159
	v_pk_add_f32 v[152:153], v[152:153], 1.0 op_sel_hi:[1,0]
	v_pk_add_f32 v[154:155], v[154:155], 1.0 op_sel_hi:[1,0]
	v_pk_add_f32 v[156:157], v[156:157], 1.0 op_sel_hi:[1,0]
	v_pk_add_f32 v[158:159], v[158:159], 1.0 op_sel_hi:[1,0]
	v_rcp_f32_e32 v152, v152
	v_rcp_f32_e32 v153, v153
	v_rcp_f32_e32 v154, v154
	v_rcp_f32_e32 v155, v155
	v_rcp_f32_e32 v156, v156
	v_rcp_f32_e32 v157, v157
	v_rcp_f32_e32 v158, v158
	v_rcp_f32_e32 v159, v159
	v_pk_mul_f32 v[152:153], v[14:15], v[152:153]
	v_pk_mul_f32 v[154:155], v[16:17], v[154:155]
	v_pk_mul_f32 v[156:157], v[10:11], v[156:157]
	v_pk_mul_f32 v[158:159], v[12:13], v[158:159]
	v_pk_mul_f32 v[152:153], v[152:153], v[6:7]
	v_pk_mul_f32 v[154:155], v[154:155], v[8:9]
	v_pk_mul_f32 v[156:157], v[156:157], v[2:3]
	v_pk_mul_f32 v[158:159], v[158:159], v[4:5]
	v_cvt_pk_bf16_f32 v2, v152, v153
	v_cvt_pk_bf16_f32 v3, v154, v155
	v_cvt_pk_bf16_f32 v4, v156, v157
	v_cvt_pk_bf16_f32 v5, v158, v159
	global_store_dwordx4 v[56:57], v[2:5], off offset:2048
	s_cbranch_vccnz .LBB0_446
	s_andn2_b64 vcc, exec, s[0:1]
	s_cbranch_vccnz .LBB0_445
	s_barrier
	s_branch .LBB0_445

.Lpk1303_exit:
	s_mov_b32 s100, 0xbfb8aa3b
	v_pk_mul_f32 v[166:167], v[126:127], s[100:101] op_sel_hi:[1,0]
	v_pk_mul_f32 v[168:169], v[128:129], s[100:101] op_sel_hi:[1,0]
	v_pk_mul_f32 v[170:171], v[122:123], s[100:101] op_sel_hi:[1,0]
	v_pk_mul_f32 v[172:173], v[124:125], s[100:101] op_sel_hi:[1,0]
	v_exp_f32_e32 v166, v166
	v_exp_f32_e32 v167, v167
	v_exp_f32_e32 v168, v168
	v_exp_f32_e32 v169, v169
	v_exp_f32_e32 v170, v170
	v_exp_f32_e32 v171, v171
	v_exp_f32_e32 v172, v172
	v_exp_f32_e32 v173, v173
	v_pk_add_f32 v[166:167], v[166:167], 1.0 op_sel_hi:[1,0]
	v_pk_add_f32 v[168:169], v[168:169], 1.0 op_sel_hi:[1,0]
	v_pk_add_f32 v[170:171], v[170:171], 1.0 op_sel_hi:[1,0]
	v_pk_add_f32 v[172:173], v[172:173], 1.0 op_sel_hi:[1,0]
	v_rcp_f32_e32 v166, v166
	v_rcp_f32_e32 v167, v167
	v_rcp_f32_e32 v168, v168
	v_rcp_f32_e32 v169, v169
	v_rcp_f32_e32 v170, v170
	v_rcp_f32_e32 v171, v171
	v_rcp_f32_e32 v172, v172
	v_rcp_f32_e32 v173, v173
	v_pk_mul_f32 v[166:167], v[126:127], v[166:167]
	v_pk_mul_f32 v[168:169], v[128:129], v[168:169]
	v_pk_mul_f32 v[170:171], v[122:123], v[170:171]
	v_pk_mul_f32 v[172:173], v[124:125], v[172:173]
	v_pk_mul_f32 v[166:167], v[166:167], v[118:119]
	v_pk_mul_f32 v[168:169], v[168:169], v[120:121]
	v_pk_mul_f32 v[170:171], v[170:171], v[114:115]
	v_pk_mul_f32 v[172:173], v[172:173], v[116:117]
	s_lshl_b32 s3, s46, 1
	s_mul_i32 s2, s24, 44
	s_or_b32 s3, s3, s41
	s_add_i32 s2, s3, s2
	s_ashr_i32 s3, s2, 31
	s_lshl_b64 s[2:3], s[2:3], 15
	v_lshl_add_u64 v[148:149], v[140:141], 0, s[2:3]
	v_cvt_pk_bf16_f32 v114, v166, v167
	v_cvt_pk_bf16_f32 v115, v168, v169
	v_cvt_pk_bf16_f32 v116, v170, v171
	v_cvt_pk_bf16_f32 v117, v172, v173
	global_store_dwordx4 v[148:149], v[114:117], off
	s_and_b64 vcc, exec, s[8:9]
	s_cbranch_vccz .LBB0_1306
	s_barrier
.LBB0_1306:
	v_pk_mul_f32 v[166:167], v[110:111], s[100:101] op_sel_hi:[1,0]
	v_pk_mul_f32 v[168:169], v[112:113], s[100:101] op_sel_hi:[1,0]
	v_pk_mul_f32 v[170:171], v[106:107], s[100:101] op_sel_hi:[1,0]
	v_pk_mul_f32 v[172:173], v[108:109], s[100:101] op_sel_hi:[1,0]
	v_exp_f32_e32 v166, v166
	v_exp_f32_e32 v167, v167
	v_exp_f32_e32 v168, v168
	v_exp_f32_e32 v169, v169
	v_exp_f32_e32 v170, v170
	v_exp_f32_e32 v171, v171
	v_exp_f32_e32 v172, v172
	v_exp_f32_e32 v173, v173
	v_pk_add_f32 v[166:167], v[166:167], 1.0 op_sel_hi:[1,0]
	v_pk_add_f32 v[168:169], v[168:169], 1.0 op_sel_hi:[1,0]
	v_pk_add_f32 v[170:171], v[170:171], 1.0 op_sel_hi:[1,0]
	v_pk_add_f32 v[172:173], v[172:173], 1.0 op_sel_hi:[1,0]
	v_rcp_f32_e32 v166, v166
	v_rcp_f32_e32 v167, v167
	v_rcp_f32_e32 v168, v168
	v_rcp_f32_e32 v169, v169
	v_rcp_f32_e32 v170, v170
	v_rcp_f32_e32 v171, v171
	v_rcp_f32_e32 v172, v172
	v_rcp_f32_e32 v173, v173
	v_pk_mul_f32 v[166:167], v[110:111], v[166:167]
	v_pk_mul_f32 v[168:169], v[112:113], v[168:169]
	v_pk_mul_f32 v[170:171], v[106:107], v[170:171]
	v_pk_mul_f32 v[172:173], v[108:109], v[172:173]
	v_pk_mul_f32 v[166:167], v[166:167], v[102:103]
	v_pk_mul_f32 v[168:169], v[168:169], v[104:105]
	v_pk_mul_f32 v[170:171], v[170:171], v[98:99]
	v_pk_mul_f32 v[172:173], v[172:173], v[100:101]
	s_mov_b64 s[2:3], -1
	v_cvt_pk_bf16_f32 v98, v166, v167
	v_cvt_pk_bf16_f32 v99, v168, v169
	v_cvt_pk_bf16_f32 v100, v170, v171
	v_cvt_pk_bf16_f32 v101, v172, v173
	global_store_dwordx4 v[148:149], v[98:101], off offset:2048
	v_pk_mul_f32 v[166:167], v[94:95], s[100:101] op_sel_hi:[1,0]
	v_pk_mul_f32 v[168:169], v[96:97], s[100:101] op_sel_hi:[1,0]
	v_pk_mul_f32 v[170:171], v[90:91], s[100:101] op_sel_hi:[1,0]
	v_pk_mul_f32 v[172:173], v[92:93], s[100:101] op_sel_hi:[1,0]
	v_exp_f32_e32 v166, v166
	v_exp_f32_e32 v167, v167
	v_exp_f32_e32 v168, v168
	v_exp_f32_e32 v169, v169
	v_exp_f32_e32 v170, v170
	v_exp_f32_e32 v171, v171
	v_exp_f32_e32 v172, v172
	v_exp_f32_e32 v173, v173
	v_pk_add_f32 v[166:167], v[166:167], 1.0 op_sel_hi:[1,0]
	v_pk_add_f32 v[168:169], v[168:169], 1.0 op_sel_hi:[1,0]
	v_pk_add_f32 v[170:171], v[170:171], 1.0 op_sel_hi:[1,0]
	v_pk_add_f32 v[172:173], v[172:173], 1.0 op_sel_hi:[1,0]
	v_rcp_f32_e32 v166, v166
	v_rcp_f32_e32 v167, v167
	v_rcp_f32_e32 v168, v168
	v_rcp_f32_e32 v169, v169
	v_rcp_f32_e32 v170, v170
	v_rcp_f32_e32 v171, v171
	v_rcp_f32_e32 v172, v172
	v_rcp_f32_e32 v173, v173
	v_pk_mul_f32 v[166:167], v[94:95], v[166:167]
	v_pk_mul_f32 v[168:169], v[96:97], v[168:169]
	v_pk_mul_f32 v[170:171], v[90:91], v[170:171]
	v_pk_mul_f32 v[172:173], v[92:93], v[172:173]
	v_pk_mul_f32 v[166:167], v[166:167], v[86:87]
	v_pk_mul_f32 v[168:169], v[168:169], v[88:89]
	v_pk_mul_f32 v[170:171], v[170:171], v[82:83]
	v_pk_mul_f32 v[172:173], v[172:173], v[84:85]
	v_add_co_u32_e32 v86, vcc, s44, v148
	s_nop 1
	v_addc_co_u32_e32 v87, vcc, 0, v149, vcc
	v_cvt_pk_bf16_f32 v82, v166, v167
	v_cvt_pk_bf16_f32 v83, v168, v169
	v_cvt_pk_bf16_f32 v84, v170, v171
	v_cvt_pk_bf16_f32 v85, v172, v173
	global_store_dwordx4 v[86:87], v[82:85], off
	v_pk_mul_f32 v[166:167], v[78:79], s[100:101] op_sel_hi:[1,0]
	v_pk_mul_f32 v[168:169], v[80:81], s[100:101] op_sel_hi:[1,0]
	v_pk_mul_f32 v[170:171], v[74:75], s[100:101] op_sel_hi:[1,0]
	v_pk_mul_f32 v[172:173], v[76:77], s[100:101] op_sel_hi:[1,0]
	v_exp_f32_e32 v166, v166
	v_exp_f32_e32 v167, v167
	v_exp_f32_e32 v168, v168
	v_exp_f32_e32 v169, v169
	v_exp_f32_e32 v170, v170
	v_exp_f32_e32 v171, v171
	v_exp_f32_e32 v172, v172
	v_exp_f32_e32 v173, v173
	v_pk_add_f32 v[166:167], v[166:167], 1.0 op_sel_hi:[1,0]
	v_pk_add_f32 v[168:169], v[168:169], 1.0 op_sel_hi:[1,0]
	v_pk_add_f32 v[170:171], v[170:171], 1.0 op_sel_hi:[1,0]
	v_pk_add_f32 v[172:173], v[172:173], 1.0 op_sel_hi:[1,0]
	v_rcp_f32_e32 v166, v166
	v_rcp_f32_e32 v167, v167
	v_rcp_f32_e32 v168, v168
	v_rcp_f32_e32 v169, v169
	v_rcp_f32_e32 v170, v170
	v_rcp_f32_e32 v171, v171
	v_rcp_f32_e32 v172, v172
	v_rcp_f32_e32 v173, v173
	v_pk_mul_f32 v[166:167], v[78:79], v[166:167]
	v_pk_mul_f32 v[168:169], v[80:81], v[168:169]
	v_pk_mul_f32 v[170:171], v[74:75], v[170:171]
	v_pk_mul_f32 v[172:173], v[76:77], v[172:173]
	v_pk_mul_f32 v[166:167], v[166:167], v[70:71]
	v_pk_mul_f32 v[168:169], v[168:169], v[72:73]
	v_pk_mul_f32 v[170:171], v[170:171], v[66:67]
	v_pk_mul_f32 v[172:173], v[172:173], v[68:69]
	v_cvt_pk_bf16_f32 v66, v166, v167
	v_cvt_pk_bf16_f32 v67, v168, v169
	v_cvt_pk_bf16_f32 v68, v170, v171
	v_cvt_pk_bf16_f32 v69, v172, v173
	global_store_dwordx4 v[86:87], v[66:69], off offset:2048
	v_pk_mul_f32 v[166:167], v[62:63], s[100:101] op_sel_hi:[1,0]
	v_pk_mul_f32 v[168:169], v[64:65], s[100:101] op_sel_hi:[1,0]
	v_pk_mul_f32 v[170:171], v[58:59], s[100:101] op_sel_hi:[1,0]
	v_pk_mul_f32 v[172:173], v[60:61], s[100:101] op_sel_hi:[1,0]
	v_exp_f32_e32 v166, v166
	v_exp_f32_e32 v167, v167
	v_exp_f32_e32 v168, v168
	v_exp_f32_e32 v169, v169
	v_exp_f32_e32 v170, v170
	v_exp_f32_e32 v171, v171
	v_exp_f32_e32 v172, v172
	v_exp_f32_e32 v173, v173
	v_pk_add_f32 v[166:167], v[166:167], 1.0 op_sel_hi:[1,0]
	v_pk_add_f32 v[168:169], v[168:169], 1.0 op_sel_hi:[1,0]
	v_pk_add_f32 v[170:171], v[170:171], 1.0 op_sel_hi:[1,0]
	v_pk_add_f32 v[172:173], v[172:173], 1.0 op_sel_hi:[1,0]
	v_rcp_f32_e32 v166, v166
	v_rcp_f32_e32 v167, v167
	v_rcp_f32_e32 v168, v168
	v_rcp_f32_e32 v169, v169
	v_rcp_f32_e32 v170, v170
	v_rcp_f32_e32 v171, v171
	v_rcp_f32_e32 v172, v172
	v_rcp_f32_e32 v173, v173
	v_pk_mul_f32 v[166:167], v[62:63], v[166:167]
	v_pk_mul_f32 v[168:169], v[64:65], v[168:169]
	v_pk_mul_f32 v[170:171], v[58:59], v[170:171]
	v_pk_mul_f32 v[172:173], v[60:61], v[172:173]
	v_pk_mul_f32 v[166:167], v[166:167], v[54:55]
	v_pk_mul_f32 v[168:169], v[168:169], v[56:57]
	v_pk_mul_f32 v[170:171], v[170:171], v[50:51]
	v_pk_mul_f32 v[172:173], v[172:173], v[52:53]
	v_add_co_u32_e32 v54, vcc, s38, v148
	s_nop 1
	v_addc_co_u32_e32 v55, vcc, 0, v149, vcc
	v_add_co_u32_e32 v56, vcc, s45, v148
	s_nop 0
	s_nop 1
	v_addc_co_u32_e32 v57, vcc, 0, v149, vcc
	v_cvt_pk_bf16_f32 v50, v166, v167
	v_cvt_pk_bf16_f32 v51, v168, v169
	v_cvt_pk_bf16_f32 v52, v170, v171
	v_cvt_pk_bf16_f32 v53, v172, v173
	global_store_dwordx4 v[56:57], v[50:53], off offset:-4096
	v_pk_mul_f32 v[166:167], v[46:47], s[100:101] op_sel_hi:[1,0]
	v_pk_mul_f32 v[168:169], v[48:49], s[100:101] op_sel_hi:[1,0]
	v_pk_mul_f32 v[170:171], v[42:43], s[100:101] op_sel_hi:[1,0]
	v_pk_mul_f32 v[172:173], v[44:45], s[100:101] op_sel_hi:[1,0]
	v_exp_f32_e32 v166, v166
	v_exp_f32_e32 v167, v167
	v_exp_f32_e32 v168, v168
	v_exp_f32_e32 v169, v169
	v_exp_f32_e32 v170, v170
	v_exp_f32_e32 v171, v171
	v_exp_f32_e32 v172, v172
	v_exp_f32_e32 v173, v173
	v_pk_add_f32 v[166:167], v[166:167], 1.0 op_sel_hi:[1,0]
	v_pk_add_f32 v[168:169], v[168:169], 1.0 op_sel_hi:[1,0]
	v_pk_add_f32 v[170:171], v[170:171], 1.0 op_sel_hi:[1,0]
	v_pk_add_f32 v[172:173], v[172:173], 1.0 op_sel_hi:[1,0]
	v_rcp_f32_e32 v166, v166
	v_rcp_f32_e32 v167, v167
	v_rcp_f32_e32 v168, v168
	v_rcp_f32_e32 v169, v169
	v_rcp_f32_e32 v170, v170
	v_rcp_f32_e32 v171, v171
	v_rcp_f32_e32 v172, v172
	v_rcp_f32_e32 v173, v173
	v_pk_mul_f32 v[166:167], v[46:47], v[166:167]
	v_pk_mul_f32 v[168:169], v[48:49], v[168:169]
	v_pk_mul_f32 v[170:171], v[42:43], v[170:171]
	v_pk_mul_f32 v[172:173], v[44:45], v[172:173]
	v_pk_mul_f32 v[166:167], v[166:167], v[38:39]
	v_pk_mul_f32 v[168:169], v[168:169], v[40:41]
	v_pk_mul_f32 v[170:171], v[170:171], v[34:35]
	v_pk_mul_f32 v[172:173], v[172:173], v[36:37]
	s_andn2_b64 vcc, exec, s[18:19]
	v_cvt_pk_bf16_f32 v34, v166, v167
	v_cvt_pk_bf16_f32 v35, v168, v169
	v_cvt_pk_bf16_f32 v36, v170, v171
	v_cvt_pk_bf16_f32 v37, v172, v173
	global_store_dwordx4 v[54:55], v[34:37], off offset:2048
	v_pk_mul_f32 v[166:167], v[30:31], s[100:101] op_sel_hi:[1,0]
	v_pk_mul_f32 v[168:169], v[32:33], s[100:101] op_sel_hi:[1,0]
	v_pk_mul_f32 v[170:171], v[26:27], s[100:101] op_sel_hi:[1,0]
	v_pk_mul_f32 v[172:173], v[28:29], s[100:101] op_sel_hi:[1,0]
	v_exp_f32_e32 v166, v166
	v_exp_f32_e32 v167, v167
	v_exp_f32_e32 v168, v168
	v_exp_f32_e32 v169, v169
	v_exp_f32_e32 v170, v170
	v_exp_f32_e32 v171, v171
	v_exp_f32_e32 v172, v172
	v_exp_f32_e32 v173, v173
	v_pk_add_f32 v[166:167], v[166:167], 1.0 op_sel_hi:[1,0]
	v_pk_add_f32 v[168:169], v[168:169], 1.0 op_sel_hi:[1,0]
	v_pk_add_f32 v[170:171], v[170:171], 1.0 op_sel_hi:[1,0]
	v_pk_add_f32 v[172:173], v[172:173], 1.0 op_sel_hi:[1,0]
	v_rcp_f32_e32 v166, v166
	v_rcp_f32_e32 v167, v167
	v_rcp_f32_e32 v168, v168
	v_rcp_f32_e32 v169, v169
	v_rcp_f32_e32 v170, v170
	v_rcp_f32_e32 v171, v171
	v_rcp_f32_e32 v172, v172
	v_rcp_f32_e32 v173, v173
	v_pk_mul_f32 v[166:167], v[30:31], v[166:167]
	v_pk_mul_f32 v[168:169], v[32:33], v[168:169]
	v_pk_mul_f32 v[170:171], v[26:27], v[170:171]
	v_pk_mul_f32 v[172:173], v[28:29], v[172:173]
	v_pk_mul_f32 v[166:167], v[166:167], v[22:23]
	v_pk_mul_f32 v[168:169], v[168:169], v[24:25]
	v_pk_mul_f32 v[170:171], v[170:171], v[18:19]
	v_pk_mul_f32 v[172:173], v[172:173], v[20:21]
	v_cvt_pk_bf16_f32 v18, v166, v167
	v_cvt_pk_bf16_f32 v19, v168, v169
	v_cvt_pk_bf16_f32 v20, v170, v171
	v_cvt_pk_bf16_f32 v21, v172, v173
	global_store_dwordx4 v[56:57], v[18:21], off
	v_pk_mul_f32 v[166:167], v[14:15], s[100:101] op_sel_hi:[1,0]
	v_pk_mul_f32 v[168:169], v[16:17], s[100:101] op_sel_hi:[1,0]
	v_pk_mul_f32 v[170:171], v[10:11], s[100:101] op_sel_hi:[1,0]
	v_pk_mul_f32 v[172:173], v[12:13], s[100:101] op_sel_hi:[1,0]
	v_exp_f32_e32 v166, v166
	v_exp_f32_e32 v167, v167
	v_exp_f32_e32 v168, v168
	v_exp_f32_e32 v169, v169
	v_exp_f32_e32 v170, v170
	v_exp_f32_e32 v171, v171
	v_exp_f32_e32 v172, v172
	v_exp_f32_e32 v173, v173
	v_pk_add_f32 v[166:167], v[166:167], 1.0 op_sel_hi:[1,0]
	v_pk_add_f32 v[168:169], v[168:169], 1.0 op_sel_hi:[1,0]
	v_pk_add_f32 v[170:171], v[170:171], 1.0 op_sel_hi:[1,0]
	v_pk_add_f32 v[172:173], v[172:173], 1.0 op_sel_hi:[1,0]
	v_rcp_f32_e32 v166, v166
	v_rcp_f32_e32 v167, v167
	v_rcp_f32_e32 v168, v168
	v_rcp_f32_e32 v169, v169
	v_rcp_f32_e32 v170, v170
	v_rcp_f32_e32 v171, v171
	v_rcp_f32_e32 v172, v172
	v_rcp_f32_e32 v173, v173
	v_pk_mul_f32 v[166:167], v[14:15], v[166:167]
	v_pk_mul_f32 v[168:169], v[16:17], v[168:169]
	v_pk_mul_f32 v[170:171], v[10:11], v[170:171]
	v_pk_mul_f32 v[172:173], v[12:13], v[172:173]
	v_pk_mul_f32 v[166:167], v[166:167], v[6:7]
	v_pk_mul_f32 v[168:169], v[168:169], v[8:9]
	v_pk_mul_f32 v[170:171], v[170:171], v[2:3]
	v_pk_mul_f32 v[172:173], v[172:173], v[4:5]
	v_cvt_pk_bf16_f32 v2, v166, v167
	v_cvt_pk_bf16_f32 v3, v168, v169
	v_cvt_pk_bf16_f32 v4, v170, v171
	v_cvt_pk_bf16_f32 v5, v172, v173
	global_store_dwordx4 v[56:57], v[2:5], off offset:2048
	s_cbranch_vccnz .LBB0_1298
	s_andn2_b64 vcc, exec, s[0:1]
	s_cbranch_vccnz .LBB0_1297
	s_barrier
	s_branch .LBB0_1297

.Lpk1400_exit:
	s_mov_b32 s100, 0xbfb8aa3b
	v_pk_mul_f32 v[152:153], v[126:127], s[100:101] op_sel_hi:[1,0]
	v_pk_mul_f32 v[154:155], v[128:129], s[100:101] op_sel_hi:[1,0]
	v_pk_mul_f32 v[156:157], v[122:123], s[100:101] op_sel_hi:[1,0]
	v_pk_mul_f32 v[158:159], v[124:125], s[100:101] op_sel_hi:[1,0]
	v_exp_f32_e32 v152, v152
	v_exp_f32_e32 v153, v153
	v_exp_f32_e32 v154, v154
	v_exp_f32_e32 v155, v155
	v_exp_f32_e32 v156, v156
	v_exp_f32_e32 v157, v157
	v_exp_f32_e32 v158, v158
	v_exp_f32_e32 v159, v159
	v_pk_add_f32 v[152:153], v[152:153], 1.0 op_sel_hi:[1,0]
	v_pk_add_f32 v[154:155], v[154:155], 1.0 op_sel_hi:[1,0]
	v_pk_add_f32 v[156:157], v[156:157], 1.0 op_sel_hi:[1,0]
	v_pk_add_f32 v[158:159], v[158:159], 1.0 op_sel_hi:[1,0]
	v_rcp_f32_e32 v152, v152
	v_rcp_f32_e32 v153, v153
	v_rcp_f32_e32 v154, v154
	v_rcp_f32_e32 v155, v155
	v_rcp_f32_e32 v156, v156
	v_rcp_f32_e32 v157, v157
	v_rcp_f32_e32 v158, v158
	v_rcp_f32_e32 v159, v159
	v_pk_mul_f32 v[152:153], v[126:127], v[152:153]
	v_pk_mul_f32 v[154:155], v[128:129], v[154:155]
	v_pk_mul_f32 v[156:157], v[122:123], v[156:157]
	v_pk_mul_f32 v[158:159], v[124:125], v[158:159]
	v_pk_mul_f32 v[152:153], v[152:153], v[118:119]
	v_pk_mul_f32 v[154:155], v[154:155], v[120:121]
	v_pk_mul_f32 v[156:157], v[156:157], v[114:115]
	v_pk_mul_f32 v[158:159], v[158:159], v[116:117]
	s_lshl_b32 s3, s24, 1
	s_mul_i32 s2, s26, 44
	s_or_b32 s3, s3, s42
	s_add_i32 s2, s3, s2
	s_ashr_i32 s3, s2, 31
	s_lshl_b64 s[2:3], s[2:3], 15
	v_lshl_add_u64 v[146:147], v[138:139], 0, s[2:3]
	v_cvt_pk_bf16_f32 v114, v152, v153
	v_cvt_pk_bf16_f32 v115, v154, v155
	v_cvt_pk_bf16_f32 v116, v156, v157
	v_cvt_pk_bf16_f32 v117, v158, v159
	global_store_dwordx4 v[146:147], v[114:117], off
	s_and_b64 vcc, exec, s[8:9]
	s_cbranch_vccz .LBB0_1403
	s_barrier
.LBB0_1403:
	v_pk_mul_f32 v[152:153], v[110:111], s[100:101] op_sel_hi:[1,0]
	v_pk_mul_f32 v[154:155], v[112:113], s[100:101] op_sel_hi:[1,0]
	v_pk_mul_f32 v[156:157], v[106:107], s[100:101] op_sel_hi:[1,0]
	v_pk_mul_f32 v[158:159], v[108:109], s[100:101] op_sel_hi:[1,0]
	v_exp_f32_e32 v152, v152
	v_exp_f32_e32 v153, v153
	v_exp_f32_e32 v154, v154
	v_exp_f32_e32 v155, v155
	v_exp_f32_e32 v156, v156
	v_exp_f32_e32 v157, v157
	v_exp_f32_e32 v158, v158
	v_exp_f32_e32 v159, v159
	v_pk_add_f32 v[152:153], v[152:153], 1.0 op_sel_hi:[1,0]
	v_pk_add_f32 v[154:155], v[154:155], 1.0 op_sel_hi:[1,0]
	v_pk_add_f32 v[156:157], v[156:157], 1.0 op_sel_hi:[1,0]
	v_pk_add_f32 v[158:159], v[158:159], 1.0 op_sel_hi:[1,0]
	v_rcp_f32_e32 v152, v152
	v_rcp_f32_e32 v153, v153
	v_rcp_f32_e32 v154, v154
	v_rcp_f32_e32 v155, v155
	v_rcp_f32_e32 v156, v156
	v_rcp_f32_e32 v157, v157
	v_rcp_f32_e32 v158, v158
	v_rcp_f32_e32 v159, v159
	v_pk_mul_f32 v[152:153], v[110:111], v[152:153]
	v_pk_mul_f32 v[154:155], v[112:113], v[154:155]
	v_pk_mul_f32 v[156:157], v[106:107], v[156:157]
	v_pk_mul_f32 v[158:159], v[108:109], v[158:159]
	v_pk_mul_f32 v[152:153], v[152:153], v[102:103]
	v_pk_mul_f32 v[154:155], v[154:155], v[104:105]
	v_pk_mul_f32 v[156:157], v[156:157], v[98:99]
	v_pk_mul_f32 v[158:159], v[158:159], v[100:101]
	s_mov_b64 s[2:3], -1
	v_cvt_pk_bf16_f32 v98, v152, v153
	v_cvt_pk_bf16_f32 v99, v154, v155
	v_cvt_pk_bf16_f32 v100, v156, v157
	v_cvt_pk_bf16_f32 v101, v158, v159
	global_store_dwordx4 v[146:147], v[98:101], off offset:2048
	v_pk_mul_f32 v[152:153], v[94:95], s[100:101] op_sel_hi:[1,0]
	v_pk_mul_f32 v[154:155], v[96:97], s[100:101] op_sel_hi:[1,0]
	v_pk_mul_f32 v[156:157], v[90:91], s[100:101] op_sel_hi:[1,0]
	v_pk_mul_f32 v[158:159], v[92:93], s[100:101] op_sel_hi:[1,0]
	v_exp_f32_e32 v152, v152
	v_exp_f32_e32 v153, v153
	v_exp_f32_e32 v154, v154
	v_exp_f32_e32 v155, v155
	v_exp_f32_e32 v156, v156
	v_exp_f32_e32 v157, v157
	v_exp_f32_e32 v158, v158
	v_exp_f32_e32 v159, v159
	v_pk_add_f32 v[152:153], v[152:153], 1.0 op_sel_hi:[1,0]
	v_pk_add_f32 v[154:155], v[154:155], 1.0 op_sel_hi:[1,0]
	v_pk_add_f32 v[156:157], v[156:157], 1.0 op_sel_hi:[1,0]
	v_pk_add_f32 v[158:159], v[158:159], 1.0 op_sel_hi:[1,0]
	v_rcp_f32_e32 v152, v152
	v_rcp_f32_e32 v153, v153
	v_rcp_f32_e32 v154, v154
	v_rcp_f32_e32 v155, v155
	v_rcp_f32_e32 v156, v156
	v_rcp_f32_e32 v157, v157
	v_rcp_f32_e32 v158, v158
	v_rcp_f32_e32 v159, v159
	v_pk_mul_f32 v[152:153], v[94:95], v[152:153]
	v_pk_mul_f32 v[154:155], v[96:97], v[154:155]
	v_pk_mul_f32 v[156:157], v[90:91], v[156:157]
	v_pk_mul_f32 v[158:159], v[92:93], v[158:159]
	v_pk_mul_f32 v[152:153], v[152:153], v[86:87]
	v_pk_mul_f32 v[154:155], v[154:155], v[88:89]
	v_pk_mul_f32 v[156:157], v[156:157], v[82:83]
	v_pk_mul_f32 v[158:159], v[158:159], v[84:85]
	v_add_co_u32_e32 v86, vcc, s45, v146
	s_nop 1
	v_addc_co_u32_e32 v87, vcc, 0, v147, vcc
	v_cvt_pk_bf16_f32 v82, v152, v153
	v_cvt_pk_bf16_f32 v83, v154, v155
	v_cvt_pk_bf16_f32 v84, v156, v157
	v_cvt_pk_bf16_f32 v85, v158, v159
	global_store_dwordx4 v[86:87], v[82:85], off
	v_pk_mul_f32 v[152:153], v[78:79], s[100:101] op_sel_hi:[1,0]
	v_pk_mul_f32 v[154:155], v[80:81], s[100:101] op_sel_hi:[1,0]
	v_pk_mul_f32 v[156:157], v[74:75], s[100:101] op_sel_hi:[1,0]
	v_pk_mul_f32 v[158:159], v[76:77], s[100:101] op_sel_hi:[1,0]
	v_exp_f32_e32 v152, v152
	v_exp_f32_e32 v153, v153
	v_exp_f32_e32 v154, v154
	v_exp_f32_e32 v155, v155
	v_exp_f32_e32 v156, v156
	v_exp_f32_e32 v157, v157
	v_exp_f32_e32 v158, v158
	v_exp_f32_e32 v159, v159
	v_pk_add_f32 v[152:153], v[152:153], 1.0 op_sel_hi:[1,0]
	v_pk_add_f32 v[154:155], v[154:155], 1.0 op_sel_hi:[1,0]
	v_pk_add_f32 v[156:157], v[156:157], 1.0 op_sel_hi:[1,0]
	v_pk_add_f32 v[158:159], v[158:159], 1.0 op_sel_hi:[1,0]
	v_rcp_f32_e32 v152, v152
	v_rcp_f32_e32 v153, v153
	v_rcp_f32_e32 v154, v154
	v_rcp_f32_e32 v155, v155
	v_rcp_f32_e32 v156, v156
	v_rcp_f32_e32 v157, v157
	v_rcp_f32_e32 v158, v158
	v_rcp_f32_e32 v159, v159
	v_pk_mul_f32 v[152:153], v[78:79], v[152:153]
	v_pk_mul_f32 v[154:155], v[80:81], v[154:155]
	v_pk_mul_f32 v[156:157], v[74:75], v[156:157]
	v_pk_mul_f32 v[158:159], v[76:77], v[158:159]
	v_pk_mul_f32 v[152:153], v[152:153], v[70:71]
	v_pk_mul_f32 v[154:155], v[154:155], v[72:73]
	v_pk_mul_f32 v[156:157], v[156:157], v[66:67]
	v_pk_mul_f32 v[158:159], v[158:159], v[68:69]
	v_cvt_pk_bf16_f32 v66, v152, v153
	v_cvt_pk_bf16_f32 v67, v154, v155
	v_cvt_pk_bf16_f32 v68, v156, v157
	v_cvt_pk_bf16_f32 v69, v158, v159
	global_store_dwordx4 v[86:87], v[66:69], off offset:2048
	v_pk_mul_f32 v[152:153], v[62:63], s[100:101] op_sel_hi:[1,0]
	v_pk_mul_f32 v[154:155], v[64:65], s[100:101] op_sel_hi:[1,0]
	v_pk_mul_f32 v[156:157], v[58:59], s[100:101] op_sel_hi:[1,0]
	v_pk_mul_f32 v[158:159], v[60:61], s[100:101] op_sel_hi:[1,0]
	v_exp_f32_e32 v152, v152
	v_exp_f32_e32 v153, v153
	v_exp_f32_e32 v154, v154
	v_exp_f32_e32 v155, v155
	v_exp_f32_e32 v156, v156
	v_exp_f32_e32 v157, v157
	v_exp_f32_e32 v158, v158
	v_exp_f32_e32 v159, v159
	v_pk_add_f32 v[152:153], v[152:153], 1.0 op_sel_hi:[1,0]
	v_pk_add_f32 v[154:155], v[154:155], 1.0 op_sel_hi:[1,0]
	v_pk_add_f32 v[156:157], v[156:157], 1.0 op_sel_hi:[1,0]
	v_pk_add_f32 v[158:159], v[158:159], 1.0 op_sel_hi:[1,0]
	v_rcp_f32_e32 v152, v152
	v_rcp_f32_e32 v153, v153
	v_rcp_f32_e32 v154, v154
	v_rcp_f32_e32 v155, v155
	v_rcp_f32_e32 v156, v156
	v_rcp_f32_e32 v157, v157
	v_rcp_f32_e32 v158, v158
	v_rcp_f32_e32 v159, v159
	v_pk_mul_f32 v[152:153], v[62:63], v[152:153]
	v_pk_mul_f32 v[154:155], v[64:65], v[154:155]
	v_pk_mul_f32 v[156:157], v[58:59], v[156:157]
	v_pk_mul_f32 v[158:159], v[60:61], v[158:159]
	v_pk_mul_f32 v[152:153], v[152:153], v[54:55]
	v_pk_mul_f32 v[154:155], v[154:155], v[56:57]
	v_pk_mul_f32 v[156:157], v[156:157], v[50:51]
	v_pk_mul_f32 v[158:159], v[158:159], v[52:53]
	v_add_co_u32_e32 v54, vcc, s39, v146
	s_nop 1
	v_addc_co_u32_e32 v55, vcc, 0, v147, vcc
	v_add_co_u32_e32 v56, vcc, s46, v146
	s_nop 0
	s_nop 1
	v_addc_co_u32_e32 v57, vcc, 0, v147, vcc
	v_cvt_pk_bf16_f32 v50, v152, v153
	v_cvt_pk_bf16_f32 v51, v154, v155
	v_cvt_pk_bf16_f32 v52, v156, v157
	v_cvt_pk_bf16_f32 v53, v158, v159
	global_store_dwordx4 v[56:57], v[50:53], off offset:-4096
	v_pk_mul_f32 v[152:153], v[46:47], s[100:101] op_sel_hi:[1,0]
	v_pk_mul_f32 v[154:155], v[48:49], s[100:101] op_sel_hi:[1,0]
	v_pk_mul_f32 v[156:157], v[42:43], s[100:101] op_sel_hi:[1,0]
	v_pk_mul_f32 v[158:159], v[44:45], s[100:101] op_sel_hi:[1,0]
	v_exp_f32_e32 v152, v152
	v_exp_f32_e32 v153, v153
	v_exp_f32_e32 v154, v154
	v_exp_f32_e32 v155, v155
	v_exp_f32_e32 v156, v156
	v_exp_f32_e32 v157, v157
	v_exp_f32_e32 v158, v158
	v_exp_f32_e32 v159, v159
	v_pk_add_f32 v[152:153], v[152:153], 1.0 op_sel_hi:[1,0]
	v_pk_add_f32 v[154:155], v[154:155], 1.0 op_sel_hi:[1,0]
	v_pk_add_f32 v[156:157], v[156:157], 1.0 op_sel_hi:[1,0]
	v_pk_add_f32 v[158:159], v[158:159], 1.0 op_sel_hi:[1,0]
	v_rcp_f32_e32 v152, v152
	v_rcp_f32_e32 v153, v153
	v_rcp_f32_e32 v154, v154
	v_rcp_f32_e32 v155, v155
	v_rcp_f32_e32 v156, v156
	v_rcp_f32_e32 v157, v157
	v_rcp_f32_e32 v158, v158
	v_rcp_f32_e32 v159, v159
	v_pk_mul_f32 v[152:153], v[46:47], v[152:153]
	v_pk_mul_f32 v[154:155], v[48:49], v[154:155]
	v_pk_mul_f32 v[156:157], v[42:43], v[156:157]
	v_pk_mul_f32 v[158:159], v[44:45], v[158:159]
	v_pk_mul_f32 v[152:153], v[152:153], v[38:39]
	v_pk_mul_f32 v[154:155], v[154:155], v[40:41]
	v_pk_mul_f32 v[156:157], v[156:157], v[34:35]
	v_pk_mul_f32 v[158:159], v[158:159], v[36:37]
	s_andn2_b64 vcc, exec, s[18:19]
	v_cvt_pk_bf16_f32 v34, v152, v153
	v_cvt_pk_bf16_f32 v35, v154, v155
	v_cvt_pk_bf16_f32 v36, v156, v157
	v_cvt_pk_bf16_f32 v37, v158, v159
	global_store_dwordx4 v[54:55], v[34:37], off offset:2048
	v_pk_mul_f32 v[152:153], v[30:31], s[100:101] op_sel_hi:[1,0]
	v_pk_mul_f32 v[154:155], v[32:33], s[100:101] op_sel_hi:[1,0]
	v_pk_mul_f32 v[156:157], v[26:27], s[100:101] op_sel_hi:[1,0]
	v_pk_mul_f32 v[158:159], v[28:29], s[100:101] op_sel_hi:[1,0]
	v_exp_f32_e32 v152, v152
	v_exp_f32_e32 v153, v153
	v_exp_f32_e32 v154, v154
	v_exp_f32_e32 v155, v155
	v_exp_f32_e32 v156, v156
	v_exp_f32_e32 v157, v157
	v_exp_f32_e32 v158, v158
	v_exp_f32_e32 v159, v159
	v_pk_add_f32 v[152:153], v[152:153], 1.0 op_sel_hi:[1,0]
	v_pk_add_f32 v[154:155], v[154:155], 1.0 op_sel_hi:[1,0]
	v_pk_add_f32 v[156:157], v[156:157], 1.0 op_sel_hi:[1,0]
	v_pk_add_f32 v[158:159], v[158:159], 1.0 op_sel_hi:[1,0]
	v_rcp_f32_e32 v152, v152
	v_rcp_f32_e32 v153, v153
	v_rcp_f32_e32 v154, v154
	v_rcp_f32_e32 v155, v155
	v_rcp_f32_e32 v156, v156
	v_rcp_f32_e32 v157, v157
	v_rcp_f32_e32 v158, v158
	v_rcp_f32_e32 v159, v159
	v_pk_mul_f32 v[152:153], v[30:31], v[152:153]
	v_pk_mul_f32 v[154:155], v[32:33], v[154:155]
	v_pk_mul_f32 v[156:157], v[26:27], v[156:157]
	v_pk_mul_f32 v[158:159], v[28:29], v[158:159]
	v_pk_mul_f32 v[152:153], v[152:153], v[22:23]
	v_pk_mul_f32 v[154:155], v[154:155], v[24:25]
	v_pk_mul_f32 v[156:157], v[156:157], v[18:19]
	v_pk_mul_f32 v[158:159], v[158:159], v[20:21]
	v_cvt_pk_bf16_f32 v18, v152, v153
	v_cvt_pk_bf16_f32 v19, v154, v155
	v_cvt_pk_bf16_f32 v20, v156, v157
	v_cvt_pk_bf16_f32 v21, v158, v159
	global_store_dwordx4 v[56:57], v[18:21], off
	v_pk_mul_f32 v[152:153], v[14:15], s[100:101] op_sel_hi:[1,0]
	v_pk_mul_f32 v[154:155], v[16:17], s[100:101] op_sel_hi:[1,0]
	v_pk_mul_f32 v[156:157], v[10:11], s[100:101] op_sel_hi:[1,0]
	v_pk_mul_f32 v[158:159], v[12:13], s[100:101] op_sel_hi:[1,0]
	v_exp_f32_e32 v152, v152
	v_exp_f32_e32 v153, v153
	v_exp_f32_e32 v154, v154
	v_exp_f32_e32 v155, v155
	v_exp_f32_e32 v156, v156
	v_exp_f32_e32 v157, v157
	v_exp_f32_e32 v158, v158
	v_exp_f32_e32 v159, v159
	v_pk_add_f32 v[152:153], v[152:153], 1.0 op_sel_hi:[1,0]
	v_pk_add_f32 v[154:155], v[154:155], 1.0 op_sel_hi:[1,0]
	v_pk_add_f32 v[156:157], v[156:157], 1.0 op_sel_hi:[1,0]
	v_pk_add_f32 v[158:159], v[158:159], 1.0 op_sel_hi:[1,0]
	v_rcp_f32_e32 v152, v152
	v_rcp_f32_e32 v153, v153
	v_rcp_f32_e32 v154, v154
	v_rcp_f32_e32 v155, v155
	v_rcp_f32_e32 v156, v156
	v_rcp_f32_e32 v157, v157
	v_rcp_f32_e32 v158, v158
	v_rcp_f32_e32 v159, v159
	v_pk_mul_f32 v[152:153], v[14:15], v[152:153]
	v_pk_mul_f32 v[154:155], v[16:17], v[154:155]
	v_pk_mul_f32 v[156:157], v[10:11], v[156:157]
	v_pk_mul_f32 v[158:159], v[12:13], v[158:159]
	v_pk_mul_f32 v[152:153], v[152:153], v[6:7]
	v_pk_mul_f32 v[154:155], v[154:155], v[8:9]
	v_pk_mul_f32 v[156:157], v[156:157], v[2:3]
	v_pk_mul_f32 v[158:159], v[158:159], v[4:5]
	v_cvt_pk_bf16_f32 v2, v152, v153
	v_cvt_pk_bf16_f32 v3, v154, v155
	v_cvt_pk_bf16_f32 v4, v156, v157
	v_cvt_pk_bf16_f32 v5, v158, v159
	global_store_dwordx4 v[56:57], v[2:5], off offset:2048
	s_cbranch_vccnz .LBB0_1395
	s_andn2_b64 vcc, exec, s[0:1]
	s_cbranch_vccnz .LBB0_1394
	s_barrier
	s_branch .LBB0_1394
